# combined-output accumulators held in free registers across the selected + own-block streams (first stash round trip removed); on top of v32
# baseline (speedup 1.0000x reference)
; #define LAS __attribute__((address_space(3)))
; __device__ __forceinline__ int launder_v(int x) { asm volatile("" : "+v"(x)); return x; }
; __device__ __forceinline__ int launder_s(int x) { x = __builtin_amdgcn_readfirstlane(x); asm volatile("" : "+s"(x)); return x; }
; template <int STG, class F>
; __device__ __forceinline__ void stream_tiles(Ctx& C, const TileSrc& src, int tile0, int ntiles, LAS unsigned char* bufs, F&& compute) {
;     ...
;     const int nst = (ntiles + STG - 1) / STG, tlast = tile0 + ntiles - 1;
;     v4u rk[STG], rv[STG];
;     { const int tidl = launder_v(C.tid);
; #pragma unroll
;       for (int h = 0; h < STG; ++h) { const int t = tile0 + h; tile_fetch(src, 64 * (t < tlast ? t : tlast), tidl, rk[h], rv[h]); }
; #pragma unroll
;       for (int h = 0; h < STG; ++h) tile_store(bufs + h * 16384, tidl, rk[h], rv[h]); }
;     __syncthreads();
; __device__ __forceinline__ void nsa_block_task(Ctx& C, int task, bf16* ONSA_OUT) {
;     ...
; #pragma unroll
;         for (int cg = 0; cg < 2; ++cg)
; #pragma unroll
;             for (int c = 0; c < 4; ++c) oc[cg][c] = o[cg][c] * g_c[cg];
;     }
;     WAVE_SYNC();
;     {
; #pragma unroll 1
;         for (int q = 0; q < 8; ++q) {
;             if (qb < 16) { if (lane < 8) SELM[q * 8 + lane] = (lane == 0) ? ((1u << (qb + 1)) - 1u) : 0u; }
;             else select_blocks(SC + q * 256, SELM + q * 8, qb - 2, qb, qb - 1, lane);
;         }
;     }
;     WAVE_SYNC();
;     LAS unsigned* ANYM = (LAS unsigned*)(C.lds + 135168 + w * 64);
;     { const int la = launder_v(lane); if (la < 16) { const int cgx = la >> 3, w8 = la & 7; ANYM[la] = SELM[(4 * cgx + 0) * 8 + w8] | SELM[(4 * cgx + 1) * 8 + w8] | SELM[(4 * cgx + 2) * 8 + w8] | SELM[(4 * cgx + 3) * 8 + w8]; } }
;     WAVE_SYNC();
;     f4* STASH = WSP(f4, WS_STASH) + (size_t)(C.bid * NWAVES + w) * 512;
; #pragma unroll
;     for (int cg = 0; cg < 2; ++cg)
; #pragma unroll
;         for (int c = 0; c < 4; ++c) STASH[(cg * 4 + c) * 64 + lane] = oc[cg][c];
;     __syncthreads();
;     {
;         AttnAcc a[2]; attn_init(a[0]); attn_init(a[1]);
;         const int kvs = launder_s(kvh);
;         const TileSrc src{WSP(bf16, WS_KS) + (size_t)kvs * RP * 64, WSP(bf16, WS_VST) + (size_t)kvs * 64 * RP, RP};
;         int cw = -1; unsigned aw0 = 0u, aw1 = 0u;
;         stream_tiles<4>(C, src, 0, qb, bufs, [&](const LAS unsigned char* buf, int j) {
.LBB0_1206:
	s_or_b64 exec, exec, s[16:17]
	v_pk_mul_f32 v[32:33], v[186:187], v[32:33] op_sel_hi:[0,1]
	v_pk_mul_f32 v[34:35], v[186:187], v[34:35] op_sel_hi:[0,1]
	s_mov_b32 s3, s97
	v_pk_mul_f32 v[48:49], v[186:187], v[48:49] op_sel_hi:[0,1]
	v_pk_mul_f32 v[50:51], v[186:187], v[50:51] op_sel_hi:[0,1]
	v_pk_mul_f32 v[44:45], v[186:187], v[44:45] op_sel_hi:[0,1]
	v_pk_mul_f32 v[46:47], v[186:187], v[46:47] op_sel_hi:[0,1]
	v_pk_mul_f32 v[36:37], v[182:183], v[36:37] op_sel_hi:[0,1]
	v_pk_mul_f32 v[38:39], v[182:183], v[38:39] op_sel_hi:[0,1]
	v_pk_mul_f32 v[40:41], v[182:183], v[40:41] op_sel_hi:[0,1]
	v_pk_mul_f32 v[42:43], v[182:183], v[42:43] op_sel_hi:[0,1]
	v_pk_mul_f32 v[28:29], v[186:187], v[28:29] op_sel_hi:[0,1]
	v_pk_mul_f32 v[30:31], v[186:187], v[30:31] op_sel_hi:[0,1]
	v_pk_mul_f32 v[20:21], v[182:183], v[20:21] op_sel_hi:[0,1]
	v_pk_mul_f32 v[22:23], v[182:183], v[22:23] op_sel_hi:[0,1]
	v_pk_mul_f32 v[24:25], v[182:183], v[24:25] op_sel_hi:[0,1]
	v_pk_mul_f32 v[26:27], v[182:183], v[26:27] op_sel_hi:[0,1]
	s_waitcnt lgkmcnt(0)
	v_mov_b64_e32 v[176:177], v[32:33]
	v_mov_b64_e32 v[178:179], v[34:35]
	v_mov_b64_e32 v[180:181], v[48:49]
	v_mov_b64_e32 v[204:205], v[50:51]
	v_mov_b64_e32 v[206:207], v[28:29]
	v_mov_b64_e32 v[208:209], v[30:31]
	v_mov_b64_e32 v[234:235], v[44:45]
	v_mov_b64_e32 v[236:237], v[46:47]
	v_mov_b64_e32 v[238:239], v[20:21]
	v_mov_b64_e32 v[240:241], v[22:23]
	v_mov_b64_e32 v[242:243], v[36:37]
	v_mov_b64_e32 v[244:245], v[38:39]
	v_mov_b64_e32 v[246:247], v[24:25]
	v_mov_b64_e32 v[248:249], v[26:27]
	v_mov_b64_e32 v[250:251], v[40:41]
	v_mov_b64_e32 v[252:253], v[42:43]
	s_waitcnt lgkmcnt(0)
	s_barrier
	s_mul_hi_i32 s17, s3, 0x208000
	s_mul_i32 s3, s3, 0x208000
	s_add_u32 s18, s79, s3
	s_addc_u32 s19, s80, s17
	s_add_u32 s16, s81, s3
	s_addc_u32 s17, s82, s17
	s_cmp_eq_u32 s94, 0
	s_mov_b32 s26, 0
	s_cbranch_scc1 .LBB0_1229
	v_mov_b32_e32 v36, v189
	s_add_i32 s3, s94, 3
	v_ashrrev_i32_e32 v20, 3, v36
	v_lshlrev_b32_e32 v28, 4, v36
	v_and_b32_e32 v0, 0x70, v28
	v_ashrrev_i32_e32 v21, 31, v20
	v_mov_b64_e32 v[22:23], s[16:17]
	v_lshl_add_u64 v[2:3], s[18:19], 0, v[0:1]
	v_mad_i64_i32 v[22:23], s[20:21], v20, s92, v[22:23]
	v_lshlrev_b64 v[24:25], 7, v[20:21]
	s_cmp_eq_u32 s0, 0
	v_lshl_add_u64 v[24:25], v[2:3], 0, v[24:25]
	s_cselect_b32 s20, 0, 64
	v_lshl_add_u64 v[22:23], v[22:23], 0, v[0:1]
	v_add_u32_e32 v24, s20, v20
	v_ashrrev_i32_e32 v25, 31, v24
	v_lshlrev_b64 v[24:25], 7, v[24:25]
	v_lshl_add_u64 v[24:25], v[2:3], 0, v[24:25]
	s_lshl_b32 s50, s20, 1
	s_min_u32 s20, s0, 2
	v_lshl_add_u64 v[26:27], v[22:23], 0, s[50:51]
	v_lshl_add_u32 v24, s20, 6, v20
	v_ashrrev_i32_e32 v25, 31, v24
	v_lshlrev_b64 v[24:25], 7, v[24:25]
	v_lshl_add_u64 v[24:25], v[2:3], 0, v[24:25]
	s_lshl_b32 s50, s20, 7
	s_min_u32 s20, s0, 3
	v_lshl_add_u64 v[26:27], v[22:23], 0, s[50:51]
	v_lshl_add_u32 v24, s20, 6, v20
	v_ashrrev_i32_e32 v25, 31, v24
	v_lshlrev_b64 v[24:25], 7, v[24:25]
	v_lshl_add_u64 v[2:3], v[2:3], 0, v[24:25]
	s_lshl_b32 s50, s20, 7
	v_lshl_add_u64 v[22:23], v[22:23], 0, s[50:51]
	v_lshrrev_b32_e32 v233, 3, v189
	v_and_b32_e32 v254, 7, v189
	v_bfe_u32 v174, v233, 1, 3
	v_xor_b32_e32 v254, v254, v174
	v_lshlrev_b32_e32 v254, 4, v254
	v_mul_lo_u32 v198, v233, s92
	v_add_u32_e32 v198, v198, v254
	v_and_b32_e32 v174, 32, v233
	v_bfe_u32 v175, v233, 2, 2
	v_lshl_or_b32 v174, v175, 3, v174
	v_bfe_u32 v175, v233, 4, 1
	v_lshl_or_b32 v174, v175, 2, v174
	v_and_or_b32 v174, v233, 3, v174
	v_lshl_add_u32 v185, v174, 7, v254
	v_readfirstlane_b32 s44, v189
	s_lshl_b32 s44, s44, 4
	s_mov_b32 s28, 0
	s_mov_b32 s3, 0
	s_add_i32 s45, s3, s44
	s_min_i32 s24, s28, s0
	s_add_i32 m0, s45, 0x0
	s_lshl_b32 s98, s24, 13
	s_add_u32 s98, s18, s98
	s_addc_u32 s99, s19, 0
	global_load_lds_dwordx4 v185, s[98:99]
	s_add_i32 m0, s45, 0x2000
	s_lshl_b32 s100, s24, 7
	s_add_u32 s100, s16, s100
	s_addc_u32 s101, s17, 0
	global_load_lds_dwordx4 v198, s[100:101]
	s_add_i32 s24, s28, 1
	s_min_i32 s24, s24, s0
	s_add_i32 m0, s45, 0x4000
	s_lshl_b32 s98, s24, 13
	s_add_u32 s98, s18, s98
	s_addc_u32 s99, s19, 0
	global_load_lds_dwordx4 v185, s[98:99]
	s_add_i32 m0, s45, 0x6000
	s_lshl_b32 s100, s24, 7
	s_add_u32 s100, s16, s100
	s_addc_u32 s101, s17, 0
	global_load_lds_dwordx4 v198, s[100:101]
	s_add_i32 s24, s28, 2
	s_min_i32 s24, s24, s0
	s_add_i32 m0, s45, 0x8000
	s_lshl_b32 s98, s24, 13
	s_add_u32 s98, s18, s98
	s_addc_u32 s99, s19, 0
	global_load_lds_dwordx4 v185, s[98:99]
	s_add_i32 m0, s45, 0xa000
	s_lshl_b32 s100, s24, 7
	s_add_u32 s100, s16, s100
	s_addc_u32 s101, s17, 0
	global_load_lds_dwordx4 v198, s[100:101]
	s_add_i32 s24, s28, 3
	s_min_i32 s24, s24, s0
	s_add_i32 m0, s45, 0xc000
	s_lshl_b32 s98, s24, 13
	s_add_u32 s98, s18, s98
	s_addc_u32 s99, s19, 0
	global_load_lds_dwordx4 v185, s[98:99]
	s_add_i32 m0, s45, 0xe000
	s_lshl_b32 s100, s24, 7
	s_add_u32 s100, s16, s100
	s_addc_u32 s101, s17, 0
	global_load_lds_dwordx4 v198, s[100:101]
	s_add_i32 s3, s94, 3
	v_lshlrev_b32_e32 v0, 2, v20
	v_lshrrev_b32_e32 v21, 1, v20
	v_mov_b32_e32 v2, v1
	v_mov_b32_e32 v3, v1
	v_and_b32_e32 v22, 35, v20
	v_lshlrev_b32_e32 v20, 7, v20
	v_bitop3_b32 v23, v28, s91, v36 bitop3:0x48
	v_and_b32_e32 v24, 16, v0
	v_and_b32_e32 v21, 12, v21
	v_add3_u32 v37, 0, v20, v23
	v_mov_b32_e32 v0, v1
	v_or3_b32 v38, v24, v22, v21
	v_mov_b64_e32 v[22:23], v[2:3]
	v_mov_b64_e32 v[26:27], v[2:3]
	v_mov_b64_e32 v[30:31], v[2:3]
	v_mov_b64_e32 v[34:35], v[2:3]
	v_mov_b64_e32 v[42:43], v[2:3]
	v_mov_b64_e32 v[46:47], v[2:3]
	v_mov_b64_e32 v[50:51], v[2:3]
	v_mov_b64_e32 v[54:55], v[2:3]
	v_mov_b64_e32 v[20:21], v[0:1]
	v_mov_b64_e32 v[24:25], v[0:1]
	v_mov_b64_e32 v[28:29], v[0:1]
	v_mov_b64_e32 v[32:33], v[0:1]
	v_mov_b64_e32 v[40:41], v[0:1]
	v_mov_b64_e32 v[44:45], v[0:1]
	v_mov_b64_e32 v[48:49], v[0:1]
	v_mov_b64_e32 v[52:53], v[0:1]
	v_lshrrev_b32_e32 v2, 1, v38
	v_xor_b32_e32 v2, v2, v36
	v_lshlrev_b32_e32 v2, 4, v2
	v_lshlrev_b32_e32 v0, 7, v38
	v_and_b32_e32 v2, 0x70, v2
	s_mov_b32 s27, 0
	v_mov_b32_e32 v169, 0xc4800000
	v_mov_b32_e32 v168, 0
	s_mov_b32 s22, -1
	s_mov_b32 s28, 0
	s_mov_b32 s31, 0
	s_mov_b32 s30, 0
	s_lshr_b32 s29, s3, 2
	v_add3_u32 v0, 0, v0, v2
	v_mov_b32_e32 v36, 0
	v_mov_b32_e32 v170, 0xc4800000
	s_mov_b32 s23, 0
	v_ashrrev_i32_e32 v226, 4, v190
	v_lshrrev_b32_e32 v225, 1, v190
	v_bitop3_b32 v233, v225, v226, 7 bitop3:0x6c
	v_lshlrev_b32_e32 v254, 7, v190
	v_add_u32_e32 v226, 4, v226
	v_lshlrev_b32_e32 v233, 4, v233
	v_and_b32_e32 v254, 0x780, v254
	v_bitop3_b32 v226, v226, v225, 7 bitop3:0x78
	v_lshlrev_b32_e32 v226, 4, v226
	v_add_u32_e32 v225, v254, v233
	v_add_u32_e32 v226, v254, v226
	s_waitcnt vmcnt(0) lgkmcnt(0)
	s_waitcnt lgkmcnt(0)
	s_barrier

; #define LAS __attribute__((address_space(3)))
; __device__ __forceinline__ bf16x8 pack8(const f4& a, const f4& b) { return __builtin_bit_cast(bf16x8, pack8u(a, b)); }
; __device__ __forceinline__ float fexp2(float x) { return __builtin_amdgcn_exp2f(x); }
; __device__ __forceinline__ int launder_s(int x) { x = __builtin_amdgcn_readfirstlane(x); asm volatile("" : "+s"(x)); return x; }
; #define MFMA16(a, b, c) __builtin_amdgcn_mfma_f32_16x16x32_bf16((a), (b), (c), 0, 0, 0)
; __device__ __forceinline__ float col_total(float l) { l += __shfl_xor(l, 16); l += __shfl_xor(l, 32); return l; }
; template <class Mask>
; __device__ __forceinline__ void attn_tile64(AttnAcc& a, const bf16x8 (&kf)[2][2][2], const bf16x8 (&vf)[2][4], const bf16x8 (&bq)[2], int kb, int fq, const Mask& mask) {
;     ...
;     float ps = 0.f; bf16x8 pb[2];
; #pragma unroll
;     for (int ch = 0; ch < 2; ++ch) { f4 p0, p1;
; #pragma unroll
;         for (int j = 0; j < 4; ++j) { p0[j] = v[ch][0][j] ? fexp2(s[ch][0][j] - a.m) : 0.f; p1[j] = v[ch][1][j] ? fexp2(s[ch][1][j] - a.m) : 0.f; ps += p0[j] + p1[j]; }
;         pb[ch] = pack8(p0, p1); }
;     a.l += ps;
; #pragma unroll
;     for (int ch = 0; ch < 2; ++ch)
; #pragma unroll
;         for (int c = 0; c < 4; ++c) a.o[c] = MFMA16(vf[ch][c], pb[ch], a.o[c]);
; __device__ __forceinline__ void nsa_block_task(Ctx& C, int task, bf16* ONSA_OUT) {
;     ...
; #pragma unroll
;         for (int cg = 0; cg < 2; ++cg) { const float lt = col_total(a[cg].l); const float sc = lt > 0.f ? g_s[cg] / lt : 0.f;
; #pragma unroll
;             for (int c = 0; c < 4; ++c) STASH[(cg * 4 + c) * 64 + lane] += a[cg].o[c] * sc; }
;     }
;     {
;         AttnAcc a[2]; attn_init(a[0]); attn_init(a[1]);
;         const int kvw = launder_s(kvh);
;         const TileSrc src{WSP(bf16, WS_KW) + (size_t)kvw * RP * 64, WSP(bf16, WS_VWT) + (size_t)kvw * 64 * RP, RP};
;         const int j0 = qb > 8 ? qb - 8 : 0;
;         const int twmin = t0 + 8 * w, twmax = twmin + 7;
;         stream_tiles<4>(C, src, j0, qb + 1 - j0, bufs, [&](const LAS unsigned char* buf, int j) {
.LBB0_1234:
	v_sub_f32_e32 v88, v88, v169
	v_exp_f32_e32 v88, v88
	v_add_f32_e32 v0, v128, v132
	v_add_f32_e32 v0, 0, v0
	v_add_f32_e32 v2, v129, v133
	v_cndmask_b32_e64 v116, v88, 0, s[28:29]
	v_sub_f32_e32 v88, v93, v169
	v_sub_f32_e32 v92, v92, v169
	v_exp_f32_e32 v88, v88
	v_add_f32_e32 v0, v2, v0
	v_add_f32_e32 v2, v130, v134
	v_exp_f32_e32 v92, v92
	v_add_f32_e32 v0, v2, v0
	v_add_f32_e32 v2, v131, v135
	v_add_f32_e32 v0, v2, v0
	v_add_f32_e32 v2, v146, v147
	v_sub_f32_e32 v89, v89, v169
	v_add_f32_e32 v0, v2, v0
	v_add_f32_e32 v2, v124, v148
	v_exp_f32_e32 v89, v89
	v_cndmask_b32_e64 v119, v88, 0, s[26:27]
	v_sub_f32_e32 v88, v90, v169
	v_add_f32_e32 v0, v2, v0
	v_add_f32_e32 v2, v125, v55
	v_cndmask_b32_e64 v117, v92, 0, s[38:39]
	v_exp_f32_e32 v92, v88
	v_sub_f32_e32 v88, v94, v169
	v_add_f32_e32 v0, v2, v0
	v_add_f32_e32 v2, v54, v126
	v_exp_f32_e32 v93, v88
	v_sub_f32_e32 v88, v91, v169
	v_add_f32_e32 v0, v2, v0
	v_exp_f32_e32 v94, v88
	v_sub_f32_e32 v88, v95, v169
	v_add_f32_e32 v3, v36, v0
	v_sub_f32_e32 v0, v120, v169
	v_sub_f32_e32 v2, v104, v169
	v_sub_f32_e32 v37, v105, v169
	v_sub_f32_e32 v55, v106, v169
	v_sub_f32_e32 v97, v107, v169
	v_cndmask_b32_e64 v118, v89, 0, s[30:31]
	s_barrier
	v_mov_b64_e32 v[100:101], v[176:177]
	v_mov_b64_e32 v[102:103], v[178:179]
	v_mov_b64_e32 v[104:105], v[180:181]
	v_mov_b64_e32 v[106:107], v[204:205]
	v_mov_b64_e32 v[108:109], v[206:207]
	v_mov_b64_e32 v[110:111], v[208:209]
	v_exp_f32_e32 v95, v88
	v_mov_b64_e32 v[88:89], v[234:235]
	v_mov_b64_e32 v[90:91], v[236:237]
	v_exp_f32_e32 v0, v0
	v_exp_f32_e32 v2, v2
	v_sub_f32_e32 v36, v121, v169
	v_sub_f32_e32 v96, v123, v169
	v_exp_f32_e32 v36, v36
	v_exp_f32_e32 v37, v37
	v_sub_f32_e32 v54, v122, v169
	v_exp_f32_e32 v96, v96
	v_exp_f32_e32 v54, v54
	v_exp_f32_e32 v55, v55
	v_exp_f32_e32 v97, v97
	v_cndmask_b32_e64 v0, v0, 0, s[44:45]
	v_cndmask_b32_e64 v2, v2, 0, s[16:17]
	v_cndmask_b32_e64 v36, 0, v36, s[46:47]
	v_cndmask_b32_e64 v37, v37, 0, s[48:49]
	v_cndmask_b32_e64 v112, v96, 0, s[36:37]
	v_cvt_pk_bf16_f32 v96, v0, v36
	v_add_f32_e32 v0, v0, v2
	v_cndmask_b32_e64 v54, v54, 0, s[34:35]
	v_cndmask_b32_e64 v55, v55, 0, s[40:41]
	v_cvt_pk_bf16_f32 v98, v2, v37
	v_add_f32_e32 v0, 0, v0
	v_add_f32_e32 v2, v36, v37
	v_cndmask_b32_e64 v113, v97, 0, s[42:43]
	v_add_f32_e32 v0, v2, v0
	v_add_f32_e32 v2, v54, v55
	v_cvt_pk_bf16_f32 v97, v54, v112
	v_cvt_pk_bf16_f32 v99, v55, v113
	v_cndmask_b32_e64 v120, v92, 0, s[18:19]
	v_cndmask_b32_e64 v121, v93, 0, s[22:23]
	v_cndmask_b32_e64 v122, v94, 0, s[20:21]
	v_cndmask_b32_e64 v123, v95, 0, s[24:25]
	v_add_f32_e32 v0, v2, v0
	v_add_f32_e32 v2, v112, v113
	v_mov_b64_e32 v[92:93], v[238:239]
	v_mov_b64_e32 v[94:95], v[240:241]
	v_mfma_f32_16x16x32_bf16 v[32:35], v[84:87], v[96:99], v[32:35]
	v_mov_b64_e32 v[84:85], v[242:243]
	v_mov_b64_e32 v[86:87], v[244:245]
	v_mov_b64_e32 v[112:113], v[250:251]
	v_mov_b64_e32 v[114:115], v[252:253]
	v_add_f32_e32 v0, v2, v0
	v_mfma_f32_16x16x32_bf16 v[28:31], v[80:83], v[96:99], v[28:31]
	v_mov_b64_e32 v[80:81], v[246:247]
	v_mov_b64_e32 v[82:83], v[248:249]
	v_add_f32_e32 v2, v116, v117
	v_add_f32_e32 v0, v2, v0
	v_add_f32_e32 v2, v118, v119
	v_add_f32_e32 v0, v2, v0
	v_add_f32_e32 v2, v120, v121
	v_add_f32_e32 v0, v2, v0
	v_add_f32_e32 v2, v122, v123
	v_add_f32_e32 v0, v2, v0
	v_add_f32_e32 v2, v168, v0
	ds_bpermute_b32 v37, v217, v3
	ds_bpermute_b32 v36, v217, v2
	v_mfma_f32_16x16x32_bf16 v[24:27], v[76:79], v[96:99], v[24:27]
	v_cvt_pk_bf16_f32 v76, v116, v118
	v_cvt_pk_bf16_f32 v77, v120, v122
	v_cvt_pk_bf16_f32 v78, v117, v119
	s_waitcnt lgkmcnt(0)
	v_pk_add_f32 v[2:3], v[2:3], v[36:37]
	ds_bpermute_b32 v37, v219, v3
	ds_bpermute_b32 v36, v219, v2
	v_mfma_f32_16x16x32_bf16 v[20:23], v[72:75], v[96:99], v[20:23]
	v_cvt_pk_bf16_f32 v79, v121, v123
	s_waitcnt lgkmcnt(0)
	v_pk_add_f32 v[2:3], v[2:3], v[36:37]
	s_nop 0
	v_div_scale_f32 v0, s[16:17], v3, v3, v187
	v_rcp_f32_e32 v36, v0
	v_mfma_f32_16x16x32_bf16 v[32:35], v[68:71], v[76:79], v[32:35]
	v_fma_f32 v37, -v0, v36, 1.0
	v_fmac_f32_e32 v36, v37, v36
	v_div_scale_f32 v37, vcc, v187, v3, v187
	v_mul_f32_e32 v54, v37, v36
	v_fma_f32 v55, -v0, v54, v37
	v_fmac_f32_e32 v54, v55, v36
	v_fma_f32 v0, -v0, v54, v37
	v_div_fmas_f32 v0, v0, v36, v54
	v_div_fixup_f32 v0, v0, v3, v187
	v_cmp_lt_f32_e32 vcc, 0, v3
	v_div_scale_f32 v3, s[16:17], v2, v2, v183
	v_rcp_f32_e32 v36, v3
	v_cndmask_b32_e32 v0, 0, v0, vcc
	s_waitcnt vmcnt(0)
	v_pk_fma_f32 v[52:53], v[52:53], v[0:1], v[102:103] op_sel_hi:[1,0,1]
	v_pk_fma_f32 v[50:51], v[50:51], v[0:1], v[100:101] op_sel_hi:[1,0,1]
	v_pk_fma_f32 v[48:49], v[48:49], v[0:1], v[106:107] op_sel_hi:[1,0,1]
	v_pk_fma_f32 v[46:47], v[46:47], v[0:1], v[104:105] op_sel_hi:[1,0,1]
	v_pk_fma_f32 v[44:45], v[44:45], v[0:1], v[110:111] op_sel_hi:[1,0,1]
	v_pk_fma_f32 v[42:43], v[42:43], v[0:1], v[108:109] op_sel_hi:[1,0,1]
	v_pk_fma_f32 v[40:41], v[40:41], v[0:1], v[90:91] op_sel_hi:[1,0,1]
	v_pk_fma_f32 v[38:39], v[38:39], v[0:1], v[88:89] op_sel_hi:[1,0,1]
	v_fma_f32 v0, -v3, v36, 1.0
	v_fmac_f32_e32 v36, v0, v36
	v_div_scale_f32 v0, vcc, v183, v2, v183
	v_mul_f32_e32 v37, v0, v36
	global_store_dwordx4 v[200:201], v[38:41], off offset:3072
	v_mfma_f32_16x16x32_bf16 v[28:31], v[64:67], v[76:79], v[28:31]
	global_store_dwordx4 v[200:201], v[50:53], off
	v_fma_f32 v38, -v3, v37, v0
	v_fmac_f32_e32 v37, v38, v36
	v_mfma_f32_16x16x32_bf16 v[24:27], v[60:63], v[76:79], v[24:27]
	v_fma_f32 v0, -v3, v37, v0
	v_div_fmas_f32 v0, v0, v36, v37
	v_div_fixup_f32 v0, v0, v2, v183
	v_mfma_f32_16x16x32_bf16 v[20:23], v[56:59], v[76:79], v[20:23]
	v_cmp_lt_f32_e32 vcc, 0, v2
	global_store_dwordx4 v[200:201], v[46:49], off offset:1024
	global_store_dwordx4 v[200:201], v[42:45], off offset:2048
	v_cndmask_b32_e32 v0, 0, v0, vcc
	v_pk_fma_f32 v[34:35], v[34:35], v[0:1], v[94:95] op_sel_hi:[1,0,1]
	v_pk_fma_f32 v[32:33], v[32:33], v[0:1], v[92:93] op_sel_hi:[1,0,1]
	v_pk_fma_f32 v[30:31], v[30:31], v[0:1], v[86:87] op_sel_hi:[1,0,1]
	v_pk_fma_f32 v[28:29], v[28:29], v[0:1], v[84:85] op_sel_hi:[1,0,1]
	v_pk_fma_f32 v[22:23], v[22:23], v[0:1], v[114:115] op_sel_hi:[1,0,1]
	v_pk_fma_f32 v[20:21], v[20:21], v[0:1], v[112:113] op_sel_hi:[1,0,1]
	v_pk_fma_f32 v[26:27], v[26:27], v[0:1], v[82:83] op_sel_hi:[1,0,1]
	v_pk_fma_f32 v[24:25], v[24:25], v[0:1], v[80:81] op_sel_hi:[1,0,1]
	v_sub_u32_e64 v0, s94, 8 clamp
	global_store_dwordx4 v[202:203], v[32:35], off
	v_readfirstlane_b32 s0, v0
	s_sub_i32 s66, s94, s0
	s_add_i32 s66, s66, 1
	s_cmp_lt_i32 s66, 1
	global_store_dwordx4 v[202:203], v[28:31], off offset:1024
	global_store_dwordx4 v[202:203], v[24:27], off offset:2048
	global_store_dwordx4 v[202:203], v[20:23], off offset:3072
	s_cbranch_scc1 .LBB0_1110
; #define LAS __attribute__((address_space(3)))
; __device__ __forceinline__ int launder_v(int x) { asm volatile("" : "+v"(x)); return x; }
; __device__ __forceinline__ int launder_s(int x) { x = __builtin_amdgcn_readfirstlane(x); asm volatile("" : "+s"(x)); return x; }
; template <int STG, class F>
; __device__ __forceinline__ void stream_tiles(Ctx& C, const TileSrc& src, int tile0, int ntiles, LAS unsigned char* bufs, F&& compute) {
;     ...
;     const int nst = (ntiles + STG - 1) / STG, tlast = tile0 + ntiles - 1;
;     v4u rk[STG], rv[STG];
;     { const int tidl = launder_v(C.tid);
; #pragma unroll
;       for (int h = 0; h < STG; ++h) { const int t = tile0 + h; tile_fetch(src, 64 * (t < tlast ? t : tlast), tidl, rk[h], rv[h]); }
; #pragma unroll
;       for (int h = 0; h < STG; ++h) tile_store(bufs + h * 16384, tidl, rk[h], rv[h]); }
;     __syncthreads();
; __device__ __forceinline__ void nsa_block_task(Ctx& C, int task, bf16* ONSA_OUT) {
;     ...
;     {
;         AttnAcc a[2]; attn_init(a[0]); attn_init(a[1]);
;         const int kvw = launder_s(kvh);
;         const TileSrc src{WSP(bf16, WS_KW) + (size_t)kvw * RP * 64, WSP(bf16, WS_VWT) + (size_t)kvw * 64 * RP, RP};
;         const int j0 = qb > 8 ? qb - 8 : 0;
;         const int twmin = t0 + 8 * w, twmax = twmin + 7;
;         stream_tiles<4>(C, src, j0, qb + 1 - j0, bufs, [&](const LAS unsigned char* buf, int j) {
	s_mul_hi_i32 s3, s97, 0x208000
	s_mul_i32 s97, s97, 0x208000
	v_readlane_b32 s16, v255, 13
	s_add_u32 s56, s16, s97
	v_readlane_b32 s16, v255, 21
	s_addc_u32 s57, s16, s3
	v_readlane_b32 s16, v255, 23
	s_add_u32 s58, s16, s97
	s_addc_u32 s59, s88, s3
	v_mov_b32_e32 v52, v189
	v_mov_b64_e32 v[20:21], s[58:59]
	v_ashrrev_i32_e32 v53, 3, v52
	v_lshlrev_b32_e32 v54, 4, v52
	v_and_b32_e32 v0, 0x70, v54
	v_mad_i64_i32 v[20:21], s[16:17], v53, s92, v[20:21]
	s_min_i32 s3, s0, s94
	v_lshl_add_u64 v[44:45], v[20:21], 0, v[0:1]
	v_lshl_add_u32 v20, s3, 6, v53
	s_lshl_b32 s50, s3, 7
	s_add_i32 s3, s0, 1
	s_min_i32 s3, s3, s94
	v_lshl_add_u64 v[24:25], v[44:45], 0, s[50:51]
	v_lshl_add_u32 v28, s3, 6, v53
	s_lshl_b32 s50, s3, 7
	s_add_i32 s3, s0, 2
	s_min_i32 s3, s3, s94
	v_lshl_add_u64 v[32:33], v[44:45], 0, s[50:51]
	v_lshl_add_u32 v36, s3, 6, v53
	s_lshl_b32 s50, s3, 7
	s_add_i32 s3, s0, 3
	s_min_i32 s3, s3, s94
	v_lshl_add_u32 v46, s3, 6, v53
	v_ashrrev_i32_e32 v21, 31, v20
	v_ashrrev_i32_e32 v29, 31, v28
	v_ashrrev_i32_e32 v37, 31, v36
	v_ashrrev_i32_e32 v47, 31, v46
	v_lshl_add_u64 v[2:3], s[56:57], 0, v[0:1]
	v_lshlrev_b64 v[20:21], 7, v[20:21]
	v_lshlrev_b64 v[28:29], 7, v[28:29]
	v_lshlrev_b64 v[36:37], 7, v[36:37]
	v_lshl_add_u64 v[40:41], v[44:45], 0, s[50:51]
	v_lshlrev_b64 v[46:47], 7, v[46:47]
	s_lshl_b32 s50, s3, 7
	v_lshl_add_u64 v[20:21], v[2:3], 0, v[20:21]
	v_lshl_add_u64 v[28:29], v[2:3], 0, v[28:29]
	v_lshl_add_u64 v[36:37], v[2:3], 0, v[36:37]
	v_lshl_add_u64 v[2:3], v[2:3], 0, v[46:47]
	v_lshl_add_u64 v[48:49], v[44:45], 0, s[50:51]
	global_load_dwordx4 v[20:23], v[20:21], off
	s_nop 0
	global_load_dwordx4 v[24:27], v[24:25], off
	s_nop 0
	global_load_dwordx4 v[28:31], v[28:29], off
	s_nop 0
	global_load_dwordx4 v[32:35], v[32:33], off
	s_nop 0
	global_load_dwordx4 v[36:39], v[36:37], off
	s_nop 0
	global_load_dwordx4 v[40:43], v[40:41], off
	s_nop 0
	global_load_dwordx4 v[44:47], v[2:3], off
	s_nop 0
	global_load_dwordx4 v[48:51], v[48:49], off
	v_lshlrev_b32_e32 v0, 2, v53
	v_lshrrev_b32_e32 v2, 1, v53
	v_and_b32_e32 v3, 35, v53
	v_and_b32_e32 v0, 16, v0
	v_and_b32_e32 v2, 12, v2
	v_or3_b32 v0, v0, v3, v2
	v_lshlrev_b32_e32 v2, 7, v0
	v_lshrrev_b32_e32 v0, 1, v0
	v_xor_b32_e32 v3, v0, v52
	v_lshlrev_b32_e32 v3, 4, v3
	v_and_b32_e32 v3, 0x70, v3
	v_lshlrev_b32_e32 v53, 7, v53
	v_bitop3_b32 v54, v54, s91, v52 bitop3:0x48
	v_add3_u32 v2, 0, v2, v3
	s_add_i32 s3, s66, 3
	v_add3_u32 v53, 0, v53, v54
	s_min_u32 s16, s94, 8
	v_mov_b32_e32 v3, v1
	s_lshr_b32 s70, s3, 2
	s_lshl_b32 s3, s16, 6
	v_mov_b32_e32 v0, v1
	v_add_u32_e32 v186, 0xfffffe00, v216
	v_add_u32_e32 v187, 0xfffffe04, v216
	s_mov_b32 s67, 0
	s_add_i32 s68, s95, 0xfffffe00
	s_add_i32 s69, s95, 0xfffffe07
	s_sub_i32 s71, s54, s3
	v_subrev_u32_e32 v233, s3, v136
	v_mov_b32_e32 v235, 0xf149f2ca
	v_mov_b32_e32 v238, 0
	s_mov_b64 s[54:55], 0
	v_mov_b32_e32 v68, 0
	v_mov_b32_e32 v234, 0
	v_mov_b32_e32 v236, 0
	v_mov_b32_e32 v237, 0xf149f2ca
	s_mov_b32 s84, 0
	s_waitcnt vmcnt(0) lgkmcnt(0)
	ds_write_b128 v2, v[20:23]
	ds_write_b128 v53, v[24:27] offset:8192
	ds_write_b128 v2, v[28:31] offset:16384
	ds_write_b128 v53, v[32:35] offset:24576
	ds_write_b128 v2, v[36:39] offset:32768
	ds_write_b128 v53, v[40:43] offset:40960
	ds_write_b128 v2, v[44:47] offset:49152
	ds_write_b128 v53, v[48:51] offset:57344
	v_mov_b32_e32 v2, v1
	v_mov_b64_e32 v[182:183], v[2:3]
	v_mov_b64_e32 v[170:171], v[2:3]
	v_mov_b64_e32 v[174:175], v[2:3]
	v_mov_b64_e32 v[178:179], v[2:3]
	v_mov_b64_e32 v[86:87], v[2:3]
	v_mov_b64_e32 v[74:75], v[2:3]
	v_mov_b64_e32 v[78:79], v[2:3]
	v_mov_b64_e32 v[82:83], v[2:3]
	v_mov_b64_e32 v[54:55], v[2:3]
	v_mov_b64_e32 v[58:59], v[2:3]
	v_mov_b64_e32 v[62:63], v[2:3]
	v_mov_b64_e32 v[66:67], v[2:3]
	v_mov_b64_e32 v[90:91], v[2:3]
	v_mov_b64_e32 v[94:95], v[2:3]
	v_mov_b64_e32 v[98:99], v[2:3]
	v_mov_b64_e32 v[102:103], v[2:3]
	v_mov_b64_e32 v[180:181], v[0:1]
	v_mov_b64_e32 v[168:169], v[0:1]
	v_mov_b64_e32 v[172:173], v[0:1]
	v_mov_b64_e32 v[176:177], v[0:1]
	v_mov_b64_e32 v[84:85], v[0:1]
	v_mov_b64_e32 v[72:73], v[0:1]
	v_mov_b64_e32 v[76:77], v[0:1]
	v_mov_b64_e32 v[80:81], v[0:1]
	v_mov_b64_e32 v[52:53], v[0:1]
	v_mov_b64_e32 v[56:57], v[0:1]
	v_mov_b64_e32 v[60:61], v[0:1]
	v_mov_b64_e32 v[64:65], v[0:1]
	v_mov_b64_e32 v[88:89], v[0:1]
	v_mov_b64_e32 v[92:93], v[0:1]
	v_mov_b64_e32 v[96:97], v[0:1]
	v_mov_b64_e32 v[100:101], v[0:1]
	s_waitcnt lgkmcnt(0)
	s_barrier
	s_branch .LBB0_1237
